# flash loops: V-fragment prefetch issued behind the row-max ds_bpermute with a counted lgkmcnt(8) instead of in front of it
# speedup vs baseline: 1.0095x; 1.0095x over previous
;     ...
;   float mx = fmaxf(S[0][0], S[0][1]);
; #pragma unroll
;   for (int ks = 0; ks < 2; ++ks)
; #pragma unroll
;     for (int i = (ks ? 0 : 2); i < 16; i += 2) mx = fmaxf(fmaxf(mx, S[ks][i]), S[ks][i + 1]);
;   mx = fmaxf(mx, __shfl_xor(mx, 32));
;   if (MODE == 2) mx = selbit ? mx : -1e30f;
;   const float mn = fmaxf(m, mx);
;   if (__any((mn - m) * c2 > 8.f)) {
;     const float alpha = __builtin_amdgcn_exp2f((m - mn) * c2);
;     m = mn;
;     l *= alpha;
; #pragma unroll
;     for (int d = 0; d < DV / 32; ++d) O[d] = O[d] * alpha;
;   }
.LBB0_360:
	s_or_b64 exec, exec, s[12:13]
	v_max_f32_e32 v104, v51, v51
	v_max_f32_e32 v117, v50, v50
	v_max_f32_e32 v104, v117, v104
	v_max3_f32 v104, v104, v52, v53
	v_max3_f32 v104, v104, v54, v55
	v_max3_f32 v104, v104, v56, v57
	v_max3_f32 v104, v104, v58, v59
	v_max3_f32 v104, v104, v60, v61
	v_max3_f32 v104, v104, v62, v63
	v_max3_f32 v104, v104, v64, v65
	v_max3_f32 v104, v104, v34, v35
	v_max3_f32 v104, v104, v36, v37
	v_max3_f32 v104, v104, v38, v39
	v_max3_f32 v104, v104, v40, v41
	v_and_b32_e32 v118, 64, v207
	v_max3_f32 v104, v104, v42, v43
	v_xor_b32_e32 v117, 32, v207
	v_add_u32_e32 v118, 64, v118
	v_max3_f32 v104, v104, v44, v45
	v_cmp_lt_i32_e32 vcc, v117, v118
	v_max3_f32 v104, v104, v46, v47
	v_max3_f32 v104, v104, v48, v49
	v_cndmask_b32_e32 v117, v207, v117, vcc
	v_lshlrev_b32_e32 v117, 2, v117
	ds_bpermute_b32 v118, v117, v104
	ds_read2_b64 v[216:219], v131 offset0:128 offset1:130
	ds_read2_b64 v[220:223], v130 offset0:192 offset1:194
	ds_read2_b64 v[224:227], v131 offset0:132 offset1:134
	ds_read2_b64 v[228:231], v130 offset0:196 offset1:198
	ds_read2_b64 v[232:235], v131 offset0:136 offset1:138
	ds_read2_b64 v[236:239], v130 offset0:200 offset1:202
	ds_read2_b64 v[240:243], v131 offset0:140 offset1:142
	ds_read2_b64 v[244:247], v130 offset0:204 offset1:206
	s_waitcnt lgkmcnt(8)
	v_max3_f32 v104, v116, v104, v118
	v_sub_f32_e32 v118, v104, v116
	v_mul_f32_e32 v118, 0x3e16c740, v118
	v_cmp_lt_f32_e32 vcc, s51, v118
	s_cbranch_vccz .LBB0_377
	v_sub_f32_e32 v116, v116, v104
	v_mul_f32_e32 v116, 0x3e16c740, v116
	v_exp_f32_e32 v116, v116
	s_nop 0
	v_mul_f32_e32 v109, v109, v116
	v_pk_mul_f32 v[16:17], v[16:17], v[116:117] op_sel_hi:[1,0]
	v_pk_mul_f32 v[14:15], v[14:15], v[116:117] op_sel_hi:[1,0]
	v_pk_mul_f32 v[12:13], v[12:13], v[116:117] op_sel_hi:[1,0]
	v_pk_mul_f32 v[10:11], v[10:11], v[116:117] op_sel_hi:[1,0]
	v_pk_mul_f32 v[8:9], v[8:9], v[116:117] op_sel_hi:[1,0]
	v_pk_mul_f32 v[6:7], v[6:7], v[116:117] op_sel_hi:[1,0]
	v_pk_mul_f32 v[4:5], v[4:5], v[116:117] op_sel_hi:[1,0]
	v_pk_mul_f32 v[2:3], v[2:3], v[116:117] op_sel_hi:[1,0]
	v_pk_mul_f32 v[32:33], v[32:33], v[116:117] op_sel_hi:[1,0]
	v_pk_mul_f32 v[30:31], v[30:31], v[116:117] op_sel_hi:[1,0]
	v_pk_mul_f32 v[28:29], v[28:29], v[116:117] op_sel_hi:[1,0]
	v_pk_mul_f32 v[26:27], v[26:27], v[116:117] op_sel_hi:[1,0]
	v_pk_mul_f32 v[24:25], v[24:25], v[116:117] op_sel_hi:[1,0]
	v_pk_mul_f32 v[22:23], v[22:23], v[116:117] op_sel_hi:[1,0]
	v_pk_mul_f32 v[20:21], v[20:21], v[116:117] op_sel_hi:[1,0]
	v_pk_mul_f32 v[18:19], v[18:19], v[116:117] op_sel_hi:[1,0]
	v_mov_b32_e32 v116, v104

; #define MFMA(a, b, c) __builtin_amdgcn_mfma_f32_32x32x16_bf16((a), (b), (c), 0, 0, 0)
; DI int crow(int i, int h) { return (i & 3) + 8 * (i >> 2) + 4 * h; }
; template <int DK, int DV, int MODE>
; DI void fa_qk(f32x16 (&S)[2], const bf16x8 (&q)[DK / 16], const char* base, int lr, int lh) {
;   using C = FA<DK, DV>;
; #pragma unroll
;   for (int ks = 0; ks < 2; ++ks) {
; #pragma unroll
;     for (int kk = 0; kk < DK / 16; ++kk) {
;       const bf16x8 kf = *(const bf16x8*)(base + (ks * 32 + lr) * C::KSTR + (kk * 2 + lh) * 16);
;       if (kk == 0) {
; #pragma unroll
;         for (int i = 0; i < 16; ++i) S[ks][i] = 0.f;
;       }
;       S[ks] = MFMA(kf, q[kk], S[ks]);
;     }
;   }
; }
;   using C = FA<DK, DV>;
;   bool selbit = true;
;   bool need_mask = false;
;   if (MODE != 0) need_mask = (kb * 64 + 63 > wave_qmax - 31);
;   if (MODE == 2) selbit = (sel >> kb) & 1ull;
;   if (MODE == 3) need_mask = need_mask || (kb * 64 <= wave_qmax - 512);
;   const float c2 = scale * 1.4426950408889634f;
;   if (need_mask) {
; #pragma unroll
;     for (int ks = 0; ks < 2; ++ks)
; #pragma unroll
;       for (int i = 0; i < 16; ++i) {
;         const int key = kb * 64 + ks * 32 + crow(i, lh);
;         bool valid = key <= qpos;
;         if (MODE == 2) valid = valid && selbit;
;         if (MODE == 3) valid = valid && (qpos - key < 512);
;         S[ks][i] = valid ? S[ks][i] : -1e30f;
;       }
.LBB0_374:
	v_cmp_le_i32_e32 vcc, s20, v110
	s_and_saveexec_b64 s[10:11], vcc
	s_cbranch_execz .LBB0_363
	s_add_i32 s6, s6, 0
	v_add3_u32 v104, s6, v112, v111
	ds_read_b128 v[34:37], v104
	ds_read_b128 v[38:41], v104 offset:32
	ds_read_b128 v[42:45], v104 offset:64
	ds_read_b128 v[46:49], v104 offset:96
	ds_read_b128 v[118:121], v104 offset:128
	ds_read_b128 v[122:125], v104 offset:160
	ds_read_b128 v[216:219], v104 offset:6656
	ds_read_b128 v[220:223], v104 offset:6688
	ds_read_b128 v[224:227], v104 offset:6720
	ds_read_b128 v[228:231], v104 offset:6752
	ds_read_b128 v[232:235], v104 offset:6784
	ds_read_b128 v[236:239], v104 offset:6816
	s_add_i32 s7, s20, 63
	v_cmp_gt_i32_e64 s[8:9], s7, v106
	v_add3_u32 v130, s6, v114, v115
	v_add_u32_e32 v131, 0x3000, v130
	v_add_u32_e32 v130, 0x4000, v130
	s_waitcnt lgkmcnt(11)
	v_mfma_f32_32x32x16_bf16 v[50:65], v[34:37], v[82:85], 0
	s_waitcnt lgkmcnt(10)
	v_mfma_f32_32x32x16_bf16 v[50:65], v[38:41], v[66:69], v[50:65]
	s_waitcnt lgkmcnt(9)
	v_mfma_f32_32x32x16_bf16 v[50:65], v[42:45], v[70:73], v[50:65]
	s_waitcnt lgkmcnt(8)
	v_mfma_f32_32x32x16_bf16 v[50:65], v[46:49], v[74:77], v[50:65]
	s_waitcnt lgkmcnt(7)
	v_mfma_f32_32x32x16_bf16 v[50:65], v[118:121], v[78:81], v[50:65]
	s_waitcnt lgkmcnt(6)
	v_mfma_f32_32x32x16_bf16 v[50:65], v[122:125], v[86:89], v[50:65]
	s_waitcnt lgkmcnt(5)
	v_mfma_f32_32x32x16_bf16 v[34:49], v[216:219], v[82:85], 0
	s_waitcnt lgkmcnt(4)
	v_mfma_f32_32x32x16_bf16 v[34:49], v[220:223], v[66:69], v[34:49]
	s_waitcnt lgkmcnt(3)
	v_mfma_f32_32x32x16_bf16 v[34:49], v[224:227], v[70:73], v[34:49]
	s_waitcnt lgkmcnt(2)
	v_mfma_f32_32x32x16_bf16 v[34:49], v[228:231], v[74:77], v[34:49]
	s_waitcnt lgkmcnt(1)
	v_mfma_f32_32x32x16_bf16 v[34:49], v[232:235], v[78:81], v[34:49]
	s_waitcnt lgkmcnt(0)
	v_mfma_f32_32x32x16_bf16 v[34:49], v[236:239], v[86:89], v[34:49]
	s_and_saveexec_b64 s[12:13], s[8:9]
	s_cbranch_execz .LBB0_360
	v_add_u32_e32 v104, s20, v113
	v_cmp_le_i32_e32 vcc, v104, v92
	v_add_u32_e32 v117, 2, v104
	s_nop 0
	v_cndmask_b32_e32 v50, v208, v50, vcc
	v_cmp_lt_i32_e32 vcc, v104, v92
	s_nop 1
	v_cndmask_b32_e32 v51, v208, v51, vcc
	v_cmp_le_i32_e32 vcc, v117, v92
	v_add_u32_e32 v117, 3, v104
	s_nop 0
	v_cndmask_b32_e32 v52, v208, v52, vcc
	v_cmp_le_i32_e32 vcc, v117, v92
	v_add_u32_e32 v117, 8, v104
	s_nop 0
	v_cndmask_b32_e32 v53, v208, v53, vcc
	v_cmp_le_i32_e32 vcc, v117, v92
	v_add_u32_e32 v117, 9, v104
	s_nop 0
	v_cndmask_b32_e32 v54, v208, v54, vcc
	v_cmp_le_i32_e32 vcc, v117, v92
	v_add_u32_e32 v117, 10, v104
	s_nop 0
	v_cndmask_b32_e32 v55, v208, v55, vcc
	v_cmp_le_i32_e32 vcc, v117, v92
	v_add_u32_e32 v117, 11, v104
	s_nop 0
	v_cndmask_b32_e32 v56, v208, v56, vcc
	v_cmp_le_i32_e32 vcc, v117, v92
	v_add_u32_e32 v117, 16, v104
	s_nop 0
	v_cndmask_b32_e32 v57, v208, v57, vcc
	v_cmp_le_i32_e32 vcc, v117, v92
	v_add_u32_e32 v117, 17, v104
	s_nop 0
	v_cndmask_b32_e32 v58, v208, v58, vcc
	v_cmp_le_i32_e32 vcc, v117, v92
	v_add_u32_e32 v117, 18, v104
	s_nop 0
	v_cndmask_b32_e32 v59, v208, v59, vcc
	v_cmp_le_i32_e32 vcc, v117, v92
	v_add_u32_e32 v117, 19, v104
	s_nop 0
	v_cndmask_b32_e32 v60, v208, v60, vcc
	v_cmp_le_i32_e32 vcc, v117, v92
	v_add_u32_e32 v117, 24, v104
	s_nop 0
	v_cndmask_b32_e32 v61, v208, v61, vcc
	v_cmp_le_i32_e32 vcc, v117, v92
	v_add_u32_e32 v117, 25, v104
	s_nop 0
	v_cndmask_b32_e32 v62, v208, v62, vcc
	v_cmp_le_i32_e32 vcc, v117, v92
	v_add_u32_e32 v117, 26, v104
	s_nop 0
	v_cndmask_b32_e32 v63, v208, v63, vcc
	v_cmp_le_i32_e32 vcc, v117, v92
	v_add_u32_e32 v117, 27, v104
	s_nop 0
	v_cndmask_b32_e32 v64, v208, v64, vcc
	v_cmp_le_i32_e32 vcc, v117, v92
	v_add_u32_e32 v117, 32, v104
	s_nop 0
	v_cndmask_b32_e32 v65, v208, v65, vcc
	v_cmp_le_i32_e32 vcc, v117, v92
	v_add_u32_e32 v117, 33, v104
	s_nop 0
	v_cndmask_b32_e32 v34, v208, v34, vcc
	v_cmp_le_i32_e32 vcc, v117, v92
	v_add_u32_e32 v117, 34, v104
	s_nop 0
	v_cndmask_b32_e32 v35, v208, v35, vcc
	v_cmp_le_i32_e32 vcc, v117, v92
	v_add_u32_e32 v117, 35, v104
	s_nop 0
	v_cndmask_b32_e32 v36, v208, v36, vcc
	v_cmp_le_i32_e32 vcc, v117, v92
	v_add_u32_e32 v117, 40, v104
	s_nop 0
	v_cndmask_b32_e32 v37, v208, v37, vcc
	v_cmp_le_i32_e32 vcc, v117, v92
	v_add_u32_e32 v117, 41, v104
	s_nop 0
	v_cndmask_b32_e32 v38, v208, v38, vcc
	v_cmp_le_i32_e32 vcc, v117, v92
	v_add_u32_e32 v117, 42, v104
	s_nop 0
	v_cndmask_b32_e32 v39, v208, v39, vcc
	v_cmp_le_i32_e32 vcc, v117, v92
	v_add_u32_e32 v117, 43, v104
	s_nop 0
	v_cndmask_b32_e32 v40, v208, v40, vcc
	v_cmp_le_i32_e32 vcc, v117, v92
	v_add_u32_e32 v117, 48, v104
	s_nop 0
	v_cndmask_b32_e32 v41, v208, v41, vcc
	v_cmp_le_i32_e32 vcc, v117, v92
	v_add_u32_e32 v117, 49, v104
	s_nop 0
	v_cndmask_b32_e32 v42, v208, v42, vcc
	v_cmp_le_i32_e32 vcc, v117, v92
	v_add_u32_e32 v117, 50, v104
	s_nop 0
	v_cndmask_b32_e32 v43, v208, v43, vcc
	v_cmp_le_i32_e32 vcc, v117, v92
	v_add_u32_e32 v117, 51, v104
	s_nop 0
	v_cndmask_b32_e32 v44, v208, v44, vcc
	v_cmp_le_i32_e32 vcc, v117, v92
	v_add_u32_e32 v117, 56, v104
	s_nop 0
	v_cndmask_b32_e32 v45, v208, v45, vcc
	v_cmp_le_i32_e32 vcc, v117, v92
	v_add_u32_e32 v117, 57, v104
	s_nop 0
	v_cndmask_b32_e32 v46, v208, v46, vcc
	v_cmp_le_i32_e32 vcc, v117, v92
	v_add_u32_e32 v117, 58, v104
	v_add_u32_e32 v104, 59, v104
	v_cndmask_b32_e32 v47, v208, v47, vcc
	v_cmp_le_i32_e32 vcc, v117, v92
	s_nop 1
	v_cndmask_b32_e32 v48, v208, v48, vcc
	v_cmp_le_i32_e32 vcc, v104, v92
	s_nop 1
	v_cndmask_b32_e32 v49, v208, v49, vcc
	s_branch .LBB0_360

; #define MFMA(a, b, c) __builtin_amdgcn_mfma_f32_32x32x16_bf16((a), (b), (c), 0, 0, 0)
; DI int crow(int i, int h) { return (i & 3) + 8 * (i >> 2) + 4 * h; }
; template <int DK, int DV, int MODE>
; DI bool fa_active(int kb, int wave_qmax, unsigned long long sel) {
;   bool active = true;
;   if (MODE != 0) active = (kb * 64 <= wave_qmax);
;   if (MODE == 2) {
;     const bool selbit = (sel >> kb) & 1ull;
;     if (__ballot(selbit) == 0ull) active = false;
;   }
;   return active;
; }
; template <int DK, int DV, int MODE>
; DI void fa_qk(f32x16 (&S)[2], const bf16x8 (&q)[DK / 16], const char* base, int lr, int lh) {
;   using C = FA<DK, DV>;
; #pragma unroll
;   for (int ks = 0; ks < 2; ++ks) {
; #pragma unroll
;     for (int kk = 0; kk < DK / 16; ++kk) {
;       const bf16x8 kf = *(const bf16x8*)(base + (ks * 32 + lr) * C::KSTR + (kk * 2 + lh) * 16);
;       if (kk == 0) {
; #pragma unroll
;         for (int i = 0; i < 16; ++i) S[ks][i] = 0.f;
;       }
;       S[ks] = MFMA(kf, q[kk], S[ks]);
;     }
;   }
; }
;   using C = FA<DK, DV>;
;   bool selbit = true;
;   bool need_mask = false;
;   if (MODE != 0) need_mask = (kb * 64 + 63 > wave_qmax - 31);
;   if (MODE == 2) selbit = (sel >> kb) & 1ull;
;   if (MODE == 3) need_mask = need_mask || (kb * 64 <= wave_qmax - 512);
;   const float c2 = scale * 1.4426950408889634f;
;   if (need_mask) {
; #pragma unroll
;     for (int ks = 0; ks < 2; ++ks)
; #pragma unroll
;       for (int i = 0; i < 16; ++i) {
;         const int key = kb * 64 + ks * 32 + crow(i, lh);
;         bool valid = key <= qpos;
;         if (MODE == 2) valid = valid && selbit;
;         if (MODE == 3) valid = valid && (qpos - key < 512);
;         S[ks][i] = valid ? S[ks][i] : -1e30f;
;       }
.LBB0_436:
	v_lshrrev_b64 v[66:67], s0, v[98:99]
	s_sub_i32 s8, s7, 63
	v_and_b32_e32 v66, 1, v66
	s_cmp_le_u32 s8, s20
	v_cmp_ne_u32_e32 vcc, 0, v66
	s_cselect_b64 s[8:9], -1, 0
	s_cmp_lg_u64 vcc, 0
	s_cselect_b64 s[10:11], -1, 0
	s_and_b64 s[8:9], s[10:11], s[8:9]
	s_andn2_b64 vcc, exec, s[8:9]
	v_cmp_eq_u32_e64 s[10:11], 1, v66
	s_cbranch_vccnz .LBB0_425
	s_add_i32 s6, s6, 0
	v_add3_u32 v110, s6, v115, v114
	ds_read_b128 v[216:219], v110
	ds_read_b128 v[220:223], v110 offset:32
	ds_read_b128 v[224:227], v110 offset:64
	ds_read_b128 v[228:231], v110 offset:96
	ds_read_b128 v[232:235], v110 offset:4608
	ds_read_b128 v[236:239], v110 offset:4640
	ds_read_b128 v[240:243], v110 offset:4672
	ds_read_b128 v[244:247], v110 offset:4704
	s_cmp_gt_u32 s7, s35
	s_cselect_b64 s[8:9], -1, 0
	s_cmp_le_u32 s7, s35
	s_waitcnt lgkmcnt(7)
	v_mfma_f32_32x32x16_bf16 v[82:97], v[216:219], v[138:141], 0
	s_waitcnt lgkmcnt(6)
	v_mfma_f32_32x32x16_bf16 v[82:97], v[220:223], v[130:133], v[82:97]
	s_waitcnt lgkmcnt(5)
	v_mfma_f32_32x32x16_bf16 v[82:97], v[224:227], v[134:137], v[82:97]
	s_waitcnt lgkmcnt(4)
	v_mfma_f32_32x32x16_bf16 v[82:97], v[228:231], v[142:145], v[82:97]
	s_waitcnt lgkmcnt(3)
	v_mfma_f32_32x32x16_bf16 v[66:81], v[232:235], v[138:141], 0
	s_waitcnt lgkmcnt(2)
	v_mfma_f32_32x32x16_bf16 v[66:81], v[236:239], v[130:133], v[66:81]
	s_waitcnt lgkmcnt(1)
	v_mfma_f32_32x32x16_bf16 v[66:81], v[240:243], v[134:137], v[66:81]
	s_waitcnt lgkmcnt(0)
	v_mfma_f32_32x32x16_bf16 v[66:81], v[244:247], v[142:145], v[66:81]
	v_add3_u32 v247, s6, v117, v115
	v_add_u32_e32 v243, 0x2000, v247
	v_add_u32_e32 v247, 0x3000, v247
	s_cbranch_scc1 .LBB0_439
	v_add_u32_e32 v110, s7, v116
	v_subrev_u32_e32 v119, 63, v110
	v_cmp_le_i32_e32 vcc, v119, v148
	s_and_b64 vcc, vcc, s[10:11]
	s_nop 0
	v_cndmask_b32_e32 v82, v208, v82, vcc
	v_cmp_lt_i32_e32 vcc, v119, v148
	s_and_b64 vcc, vcc, s[10:11]
	v_subrev_u32_e32 v119, 61, v110
	v_cndmask_b32_e32 v83, v208, v83, vcc
	v_cmp_le_i32_e32 vcc, v119, v148
	s_and_b64 vcc, vcc, s[10:11]
	v_subrev_u32_e32 v119, 60, v110
	v_cndmask_b32_e32 v84, v208, v84, vcc
	v_cmp_le_i32_e32 vcc, v119, v148
	s_and_b64 vcc, vcc, s[10:11]
	v_subrev_u32_e32 v119, 55, v110
	v_cndmask_b32_e32 v85, v208, v85, vcc
	v_cmp_le_i32_e32 vcc, v119, v148
	s_and_b64 vcc, vcc, s[10:11]
	v_subrev_u32_e32 v119, 54, v110
	v_cndmask_b32_e32 v86, v208, v86, vcc
	v_cmp_le_i32_e32 vcc, v119, v148
	s_and_b64 vcc, vcc, s[10:11]
	v_subrev_u32_e32 v119, 53, v110
	v_cndmask_b32_e32 v87, v208, v87, vcc
	v_cmp_le_i32_e32 vcc, v119, v148
	s_and_b64 vcc, vcc, s[10:11]
	v_subrev_u32_e32 v119, 52, v110
	v_cndmask_b32_e32 v88, v208, v88, vcc
	v_cmp_le_i32_e32 vcc, v119, v148
	s_and_b64 vcc, vcc, s[10:11]
	v_subrev_u32_e32 v119, 47, v110
	v_cndmask_b32_e32 v89, v208, v89, vcc
	v_cmp_le_i32_e32 vcc, v119, v148
	s_and_b64 vcc, vcc, s[10:11]
	v_subrev_u32_e32 v119, 46, v110
	v_cndmask_b32_e32 v90, v208, v90, vcc
	v_cmp_le_i32_e32 vcc, v119, v148
	s_and_b64 vcc, vcc, s[10:11]
	v_subrev_u32_e32 v119, 45, v110
	v_cndmask_b32_e32 v91, v208, v91, vcc
	v_cmp_le_i32_e32 vcc, v119, v148
	s_and_b64 vcc, vcc, s[10:11]
	v_subrev_u32_e32 v119, 44, v110
	v_cndmask_b32_e32 v92, v208, v92, vcc
	v_cmp_le_i32_e32 vcc, v119, v148
	s_and_b64 vcc, vcc, s[10:11]
	v_subrev_u32_e32 v119, 39, v110
	v_cndmask_b32_e32 v93, v208, v93, vcc
	v_cmp_le_i32_e32 vcc, v119, v148
	s_and_b64 vcc, vcc, s[10:11]
	v_subrev_u32_e32 v119, 38, v110
	v_cndmask_b32_e32 v94, v208, v94, vcc
	v_cmp_le_i32_e32 vcc, v119, v148
	s_and_b64 vcc, vcc, s[10:11]
	v_subrev_u32_e32 v119, 37, v110
	v_cndmask_b32_e32 v95, v208, v95, vcc
	v_cmp_le_i32_e32 vcc, v119, v148
	s_and_b64 vcc, vcc, s[10:11]
	v_subrev_u32_e32 v119, 36, v110
	v_cndmask_b32_e32 v96, v208, v96, vcc
	v_cmp_le_i32_e32 vcc, v119, v148
	s_and_b64 vcc, vcc, s[10:11]
	v_subrev_u32_e32 v119, 31, v110
	v_cndmask_b32_e32 v97, v208, v97, vcc
	v_cmp_le_i32_e32 vcc, v119, v148
	s_and_b64 vcc, vcc, s[10:11]
	v_subrev_u32_e32 v119, 30, v110
	v_cndmask_b32_e32 v66, v208, v66, vcc
	v_cmp_le_i32_e32 vcc, v119, v148
	s_and_b64 vcc, vcc, s[10:11]
	v_subrev_u32_e32 v119, 29, v110
	v_cndmask_b32_e32 v67, v208, v67, vcc
	v_cmp_le_i32_e32 vcc, v119, v148
	s_and_b64 vcc, vcc, s[10:11]
	v_subrev_u32_e32 v119, 28, v110
	v_cndmask_b32_e32 v68, v208, v68, vcc
	v_cmp_le_i32_e32 vcc, v119, v148
	s_and_b64 vcc, vcc, s[10:11]
	v_subrev_u32_e32 v119, 23, v110
	v_cndmask_b32_e32 v69, v208, v69, vcc
	v_cmp_le_i32_e32 vcc, v119, v148
	s_and_b64 vcc, vcc, s[10:11]
	v_subrev_u32_e32 v119, 22, v110
	v_cndmask_b32_e32 v70, v208, v70, vcc
	v_cmp_le_i32_e32 vcc, v119, v148
	s_and_b64 vcc, vcc, s[10:11]
	v_subrev_u32_e32 v119, 21, v110
	v_cndmask_b32_e32 v71, v208, v71, vcc
	v_cmp_le_i32_e32 vcc, v119, v148
	s_and_b64 vcc, vcc, s[10:11]
	v_subrev_u32_e32 v119, 20, v110
	v_cndmask_b32_e32 v72, v208, v72, vcc
	v_cmp_le_i32_e32 vcc, v119, v148
	s_and_b64 vcc, vcc, s[10:11]
	v_add_u32_e32 v119, -15, v110
	v_cndmask_b32_e32 v73, v208, v73, vcc
	v_cmp_le_i32_e32 vcc, v119, v148
	s_and_b64 vcc, vcc, s[10:11]
	v_add_u32_e32 v119, -14, v110
	v_cndmask_b32_e32 v74, v208, v74, vcc
	v_cmp_le_i32_e32 vcc, v119, v148
	s_and_b64 vcc, vcc, s[10:11]
	v_add_u32_e32 v119, -13, v110
	v_cndmask_b32_e32 v75, v208, v75, vcc
	v_cmp_le_i32_e32 vcc, v119, v148
	s_and_b64 vcc, vcc, s[10:11]
	v_add_u32_e32 v119, -12, v110
	v_cndmask_b32_e32 v76, v208, v76, vcc
	v_cmp_le_i32_e32 vcc, v119, v148
	s_and_b64 vcc, vcc, s[10:11]
	v_add_u32_e32 v119, -7, v110
	v_cndmask_b32_e32 v77, v208, v77, vcc
	v_cmp_le_i32_e32 vcc, v119, v148
	s_and_b64 vcc, vcc, s[10:11]
	v_add_u32_e32 v119, -6, v110
	v_cndmask_b32_e32 v78, v208, v78, vcc
	v_cmp_le_i32_e32 vcc, v119, v148
	s_and_b64 vcc, vcc, s[10:11]
	v_add_u32_e32 v119, -5, v110
	v_cndmask_b32_e32 v79, v208, v79, vcc
	v_cmp_le_i32_e32 vcc, v119, v148
	s_and_b64 vcc, vcc, s[10:11]
	v_add_u32_e32 v110, -4, v110
	v_cndmask_b32_e32 v80, v208, v80, vcc
	v_cmp_le_i32_e32 vcc, v110, v148
	s_and_b64 vcc, vcc, s[10:11]
	s_nop 0
	v_cndmask_b32_e32 v81, v208, v81, vcc
;     ...
;   float mx = fmaxf(S[0][0], S[0][1]);
; #pragma unroll
;   for (int ks = 0; ks < 2; ++ks)
; #pragma unroll
;     for (int i = (ks ? 0 : 2); i < 16; i += 2) mx = fmaxf(fmaxf(mx, S[ks][i]), S[ks][i + 1]);
;   mx = fmaxf(mx, __shfl_xor(mx, 32));
;   if (MODE == 2) mx = selbit ? mx : -1e30f;
;   const float mn = fmaxf(m, mx);
;   if (__any((mn - m) * c2 > 8.f)) {
.LBB0_439:
	s_nop 0
	v_max_f32_e32 v110, v83, v83
	v_max_f32_e32 v119, v82, v82
	v_max_f32_e32 v110, v119, v110
	v_max3_f32 v110, v110, v84, v85
	v_max3_f32 v110, v110, v86, v87
	v_max3_f32 v110, v110, v88, v89
	v_max3_f32 v110, v110, v90, v91
	v_max3_f32 v110, v110, v92, v93
	v_max3_f32 v110, v110, v94, v95
	v_max3_f32 v110, v110, v96, v97
	v_max3_f32 v110, v110, v66, v67
	v_max3_f32 v110, v110, v68, v69
	v_max3_f32 v110, v110, v70, v71
	v_max3_f32 v110, v110, v72, v73
	v_max3_f32 v110, v110, v74, v75
	v_max3_f32 v110, v110, v76, v77
	v_max3_f32 v110, v110, v78, v79
	v_max3_f32 v110, v110, v80, v81
	ds_bpermute_b32 v119, v165, v110
	ds_read2_b64 v[216:219], v243 offset0:128 offset1:130
	ds_read2_b64 v[220:223], v247 offset0:192 offset1:194
	ds_read2_b64 v[224:227], v243 offset0:132 offset1:134
	ds_read2_b64 v[228:231], v247 offset0:196 offset1:198
	ds_read2_b64 v[232:235], v243 offset0:136 offset1:138
	ds_read2_b64 v[236:239], v247 offset0:200 offset1:202
	ds_read2_b64 v[240:243], v243 offset0:140 offset1:142
	ds_read2_b64 v[244:247], v247 offset0:204 offset1:206
	s_waitcnt lgkmcnt(8)
	v_max_f32_e32 v119, v119, v119
	v_max_f32_e32 v110, v110, v119
	v_cndmask_b32_e64 v110, v208, v110, s[10:11]
	v_max_f32_e32 v119, v118, v118
	v_max_f32_e32 v110, v119, v110
	v_sub_f32_e32 v119, v110, v118
	v_mul_f32_e32 v119, 0x3e38aa3b, v119
	v_cmp_lt_f32_e32 vcc, s51, v119
	s_cbranch_vccnz .LBB0_423
	v_mov_b32_e32 v110, v118
	s_branch .LBB0_424

; #define MFMA(a, b, c) __builtin_amdgcn_mfma_f32_32x32x16_bf16((a), (b), (c), 0, 0, 0)
; template <int DK, int DV, int MODE>
; DI void fa_qk(f32x16 (&S)[2], const bf16x8 (&q)[DK / 16], const char* base, int lr, int lh) {
;   using C = FA<DK, DV>;
; #pragma unroll
;   for (int ks = 0; ks < 2; ++ks) {
; #pragma unroll
;     for (int kk = 0; kk < DK / 16; ++kk) {
;       const bf16x8 kf = *(const bf16x8*)(base + (ks * 32 + lr) * C::KSTR + (kk * 2 + lh) * 16);
;       if (kk == 0) {
; #pragma unroll
;         for (int i = 0; i < 16; ++i) S[ks][i] = 0.f;
;       }
;       S[ks] = MFMA(kf, q[kk], S[ks]);
;     }
;   }
; }
.LBB0_467:
	s_add_i32 s6, s38, s17
	s_add_i32 s1, s6, 0xdc0
	s_cmp_gt_u32 s1, s20
	s_cbranch_scc1 .LBB0_456
	s_add_i32 s0, s0, 0
	v_add3_u32 v162, s0, v174, v173
	ds_read_b128 v[216:219], v162
	ds_read_b128 v[220:223], v162 offset:32
	ds_read_b128 v[224:227], v162 offset:64
	ds_read_b128 v[228:231], v162 offset:96
	ds_read_b128 v[232:235], v162 offset:4608
	ds_read_b128 v[236:239], v162 offset:4640
	ds_read_b128 v[240:243], v162 offset:4672
	ds_read_b128 v[244:247], v162 offset:4704
	s_addk_i32 s6, 0xddf
	s_cmp_gt_u32 s6, s45
	s_cselect_b64 s[8:9], -1, 0
	s_cmp_le_i32 s1, s16
	s_cselect_b64 s[10:11], -1, 0
	s_or_b64 s[8:9], s[8:9], s[10:11]
	s_andn2_b64 vcc, exec, s[8:9]
	s_waitcnt lgkmcnt(7)
	v_mfma_f32_32x32x16_bf16 v[114:129], v[216:219], v[138:141], 0
	s_waitcnt lgkmcnt(6)
	v_mfma_f32_32x32x16_bf16 v[114:129], v[220:223], v[130:133], v[114:129]
	s_waitcnt lgkmcnt(5)
	v_mfma_f32_32x32x16_bf16 v[114:129], v[224:227], v[134:137], v[114:129]
	s_waitcnt lgkmcnt(4)
	v_mfma_f32_32x32x16_bf16 v[114:129], v[228:231], v[142:145], v[114:129]
	s_waitcnt lgkmcnt(3)
	v_mfma_f32_32x32x16_bf16 v[98:113], v[232:235], v[138:141], 0
	s_waitcnt lgkmcnt(2)
	v_mfma_f32_32x32x16_bf16 v[98:113], v[236:239], v[130:133], v[98:113]
	s_waitcnt lgkmcnt(1)
	v_mfma_f32_32x32x16_bf16 v[98:113], v[240:243], v[134:137], v[98:113]
	s_waitcnt lgkmcnt(0)
	v_mfma_f32_32x32x16_bf16 v[98:113], v[244:247], v[142:145], v[98:113]
	v_add3_u32 v247, s0, v176, v174
	v_add_u32_e32 v243, 0x2000, v247
	v_add_u32_e32 v247, 0x3000, v247
	s_cbranch_vccnz .LBB0_470
; DI int crow(int i, int h) { return (i & 3) + 8 * (i >> 2) + 4 * h; }
;     ...
;     for (int ks = 0; ks < 2; ++ks)
; #pragma unroll
;       for (int i = 0; i < 16; ++i) {
;         const int key = kb * 64 + ks * 32 + crow(i, lh);
;         bool valid = key <= qpos;
;         if (MODE == 2) valid = valid && selbit;
;         if (MODE == 3) valid = valid && (qpos - key < 512);
;         S[ks][i] = valid ? S[ks][i] : -1e30f;
;       }
;   }
;   float mx = fmaxf(S[0][0], S[0][1]);
; #pragma unroll
;   for (int ks = 0; ks < 2; ++ks)
; #pragma unroll
;     for (int i = (ks ? 0 : 2); i < 16; i += 2) mx = fmaxf(fmaxf(mx, S[ks][i]), S[ks][i + 1]);
;   mx = fmaxf(mx, __shfl_xor(mx, 32));
;   if (MODE == 2) mx = selbit ? mx : -1e30f;
;   const float mn = fmaxf(m, mx);
;   if (__any((mn - m) * c2 > 8.f)) {
	v_add_u32_e32 v162, s17, v177
	v_add_u32_e32 v179, 0xdc0, v162
	v_cmp_le_i32_e32 vcc, v179, v148
	v_cmp_gt_i32_e64 s[10:11], v179, v175
	s_and_b64 vcc, vcc, s[10:11]
	v_cndmask_b32_e32 v114, v208, v114, vcc
	v_cmp_lt_i32_e32 vcc, v179, v148
	v_cmp_ge_i32_e64 s[10:11], v179, v175
	s_and_b64 vcc, vcc, s[10:11]
	v_add_u32_e32 v179, 0xdc2, v162
	v_cndmask_b32_e32 v115, v208, v115, vcc
	v_cmp_le_i32_e32 vcc, v179, v148
	v_cmp_gt_i32_e64 s[10:11], v179, v175
	s_and_b64 vcc, vcc, s[10:11]
	v_add_u32_e32 v179, 0xdc3, v162
	v_cndmask_b32_e32 v116, v208, v116, vcc
	v_cmp_le_i32_e32 vcc, v179, v148
	v_cmp_gt_i32_e64 s[10:11], v179, v175
	s_and_b64 vcc, vcc, s[10:11]
	v_add_u32_e32 v179, 0xdc8, v162
	v_cndmask_b32_e32 v117, v208, v117, vcc
	v_cmp_le_i32_e32 vcc, v179, v148
	v_cmp_gt_i32_e64 s[10:11], v179, v175
	s_and_b64 vcc, vcc, s[10:11]
	v_add_u32_e32 v179, 0xdc9, v162
	v_cndmask_b32_e32 v118, v208, v118, vcc
	v_cmp_le_i32_e32 vcc, v179, v148
	v_cmp_gt_i32_e64 s[10:11], v179, v175
	s_and_b64 vcc, vcc, s[10:11]
	v_add_u32_e32 v179, 0xdca, v162
	v_cndmask_b32_e32 v119, v208, v119, vcc
	v_cmp_le_i32_e32 vcc, v179, v148
	v_cmp_gt_i32_e64 s[10:11], v179, v175
	s_and_b64 vcc, vcc, s[10:11]
	v_add_u32_e32 v179, 0xdcb, v162
	v_cndmask_b32_e32 v120, v208, v120, vcc
	v_cmp_le_i32_e32 vcc, v179, v148
	v_cmp_gt_i32_e64 s[10:11], v179, v175
	s_and_b64 vcc, vcc, s[10:11]
	v_add_u32_e32 v179, 0xdd0, v162
	v_cndmask_b32_e32 v121, v208, v121, vcc
	v_cmp_le_i32_e32 vcc, v179, v148
	v_cmp_gt_i32_e64 s[10:11], v179, v175
	s_and_b64 vcc, vcc, s[10:11]
	v_add_u32_e32 v179, 0xdd1, v162
	v_cndmask_b32_e32 v122, v208, v122, vcc
	v_cmp_le_i32_e32 vcc, v179, v148
	v_cmp_gt_i32_e64 s[10:11], v179, v175
	s_and_b64 vcc, vcc, s[10:11]
	v_add_u32_e32 v179, 0xdd2, v162
	v_cndmask_b32_e32 v123, v208, v123, vcc
	v_cmp_le_i32_e32 vcc, v179, v148
	v_cmp_gt_i32_e64 s[10:11], v179, v175
	s_and_b64 vcc, vcc, s[10:11]
	v_add_u32_e32 v179, 0xdd3, v162
	v_cndmask_b32_e32 v124, v208, v124, vcc
	v_cmp_le_i32_e32 vcc, v179, v148
	v_cmp_gt_i32_e64 s[10:11], v179, v175
	s_and_b64 vcc, vcc, s[10:11]
	v_add_u32_e32 v179, 0xdd8, v162
	v_cndmask_b32_e32 v125, v208, v125, vcc
	v_cmp_le_i32_e32 vcc, v179, v148
	v_cmp_gt_i32_e64 s[10:11], v179, v175
	s_and_b64 vcc, vcc, s[10:11]
	v_add_u32_e32 v179, 0xdd9, v162
	v_cndmask_b32_e32 v126, v208, v126, vcc
	v_cmp_le_i32_e32 vcc, v179, v148
	v_cmp_gt_i32_e64 s[10:11], v179, v175
	s_and_b64 vcc, vcc, s[10:11]
	v_add_u32_e32 v179, 0xdda, v162
	v_cndmask_b32_e32 v127, v208, v127, vcc
	v_cmp_le_i32_e32 vcc, v179, v148
	v_cmp_gt_i32_e64 s[10:11], v179, v175
	s_and_b64 vcc, vcc, s[10:11]
	v_add_u32_e32 v179, 0xddb, v162
	v_cndmask_b32_e32 v128, v208, v128, vcc
	v_cmp_le_i32_e32 vcc, v179, v148
	v_cmp_gt_i32_e64 s[10:11], v179, v175
	s_and_b64 vcc, vcc, s[10:11]
	v_add_u32_e32 v179, 0xde0, v162
	v_cndmask_b32_e32 v129, v208, v129, vcc
	v_cmp_le_i32_e32 vcc, v179, v148
	v_cmp_gt_i32_e64 s[10:11], v179, v175
	s_and_b64 vcc, vcc, s[10:11]
	v_add_u32_e32 v179, 0xde1, v162
	v_cndmask_b32_e32 v98, v208, v98, vcc
	v_cmp_le_i32_e32 vcc, v179, v148
	v_cmp_gt_i32_e64 s[10:11], v179, v175
	s_and_b64 vcc, vcc, s[10:11]
	v_add_u32_e32 v179, 0xde2, v162
	v_cndmask_b32_e32 v99, v208, v99, vcc
	v_cmp_le_i32_e32 vcc, v179, v148
	v_cmp_gt_i32_e64 s[10:11], v179, v175
	s_and_b64 vcc, vcc, s[10:11]
	v_add_u32_e32 v179, 0xde3, v162
	v_cndmask_b32_e32 v100, v208, v100, vcc
	v_cmp_le_i32_e32 vcc, v179, v148
	v_cmp_gt_i32_e64 s[10:11], v179, v175
	s_and_b64 vcc, vcc, s[10:11]
	v_add_u32_e32 v179, 0xde8, v162
	v_cndmask_b32_e32 v101, v208, v101, vcc
	v_cmp_le_i32_e32 vcc, v179, v148
	v_cmp_gt_i32_e64 s[10:11], v179, v175
	s_and_b64 vcc, vcc, s[10:11]
	v_add_u32_e32 v179, 0xde9, v162
	v_cndmask_b32_e32 v102, v208, v102, vcc
	v_cmp_le_i32_e32 vcc, v179, v148
	v_cmp_gt_i32_e64 s[10:11], v179, v175
	s_and_b64 vcc, vcc, s[10:11]
	v_add_u32_e32 v179, 0xdea, v162
	v_cndmask_b32_e32 v103, v208, v103, vcc
	v_cmp_le_i32_e32 vcc, v179, v148
	v_cmp_gt_i32_e64 s[10:11], v179, v175
	s_and_b64 vcc, vcc, s[10:11]
	v_add_u32_e32 v179, 0xdeb, v162
	v_cndmask_b32_e32 v104, v208, v104, vcc
	v_cmp_le_i32_e32 vcc, v179, v148
	v_cmp_gt_i32_e64 s[10:11], v179, v175
	s_and_b64 vcc, vcc, s[10:11]
	v_add_u32_e32 v179, 0xdf0, v162
	v_cndmask_b32_e32 v105, v208, v105, vcc
	v_cmp_le_i32_e32 vcc, v179, v148
	v_cmp_gt_i32_e64 s[10:11], v179, v175
	s_and_b64 vcc, vcc, s[10:11]
	v_add_u32_e32 v179, 0xdf1, v162
	v_cndmask_b32_e32 v106, v208, v106, vcc
	v_cmp_le_i32_e32 vcc, v179, v148
	v_cmp_gt_i32_e64 s[10:11], v179, v175
	s_and_b64 vcc, vcc, s[10:11]
	v_add_u32_e32 v179, 0xdf2, v162
	v_cndmask_b32_e32 v107, v208, v107, vcc
	v_cmp_le_i32_e32 vcc, v179, v148
	v_cmp_gt_i32_e64 s[10:11], v179, v175
	s_and_b64 vcc, vcc, s[10:11]
	v_add_u32_e32 v179, 0xdf3, v162
	v_cndmask_b32_e32 v108, v208, v108, vcc
	v_cmp_le_i32_e32 vcc, v179, v148
	v_cmp_gt_i32_e64 s[10:11], v179, v175
	s_and_b64 vcc, vcc, s[10:11]
	v_add_u32_e32 v179, 0xdf8, v162
	v_cndmask_b32_e32 v109, v208, v109, vcc
	v_cmp_le_i32_e32 vcc, v179, v148
	v_cmp_gt_i32_e64 s[10:11], v179, v175
	s_and_b64 vcc, vcc, s[10:11]
	v_add_u32_e32 v179, 0xdf9, v162
	v_cndmask_b32_e32 v110, v208, v110, vcc
	v_cmp_le_i32_e32 vcc, v179, v148
	v_cmp_gt_i32_e64 s[10:11], v179, v175
	s_and_b64 vcc, vcc, s[10:11]
	v_add_u32_e32 v179, 0xdfa, v162
	v_cndmask_b32_e32 v111, v208, v111, vcc
	v_cmp_le_i32_e32 vcc, v179, v148
	v_cmp_gt_i32_e64 s[10:11], v179, v175
	s_and_b64 vcc, vcc, s[10:11]
	v_add_u32_e32 v162, 0xdfb, v162
	v_cndmask_b32_e32 v112, v208, v112, vcc
	v_cmp_le_i32_e32 vcc, v162, v148
	v_cmp_gt_i32_e64 s[10:11], v162, v175
	s_and_b64 vcc, vcc, s[10:11]
	v_cndmask_b32_e32 v113, v208, v113, vcc
.LBB0_470:
	s_nop 0
	v_max_f32_e32 v162, v115, v115
	v_max_f32_e32 v179, v114, v114
	v_max_f32_e32 v162, v179, v162
	v_max3_f32 v162, v162, v116, v117
	v_max3_f32 v162, v162, v118, v119
	v_max3_f32 v162, v162, v120, v121
	v_max3_f32 v162, v162, v122, v123
	v_max3_f32 v162, v162, v124, v125
	v_max3_f32 v162, v162, v126, v127
	v_max3_f32 v162, v162, v128, v129
	v_max3_f32 v162, v162, v98, v99
	v_max3_f32 v162, v162, v100, v101
	v_max3_f32 v162, v162, v102, v103
	v_max3_f32 v162, v162, v104, v105
	v_max3_f32 v162, v162, v106, v107
	v_max3_f32 v162, v162, v108, v109
	v_max3_f32 v162, v162, v110, v111
	v_max3_f32 v162, v162, v112, v113
	ds_bpermute_b32 v179, v165, v162
	ds_read2_b64 v[216:219], v243 offset0:128 offset1:130
	ds_read2_b64 v[220:223], v247 offset0:192 offset1:194
	ds_read2_b64 v[224:227], v243 offset0:132 offset1:134
	ds_read2_b64 v[228:231], v247 offset0:196 offset1:198
	ds_read2_b64 v[232:235], v243 offset0:136 offset1:138
	ds_read2_b64 v[236:239], v247 offset0:200 offset1:202
	ds_read2_b64 v[240:243], v243 offset0:140 offset1:142
	ds_read2_b64 v[244:247], v247 offset0:204 offset1:206
	s_waitcnt lgkmcnt(8)
	v_max3_f32 v162, v178, v162, v179
	v_sub_f32_e32 v179, v162, v178
	v_mul_f32_e32 v179, 0x3e38aa3b, v179
	v_cmp_lt_f32_e32 vcc, s51, v179
	s_cbranch_vccnz .LBB0_454
	v_mov_b32_e32 v162, v178
	s_branch .LBB0_455

;     ...
;   float mx = fmaxf(S[0][0], S[0][1]);
; #pragma unroll
;   for (int ks = 0; ks < 2; ++ks)
; #pragma unroll
;     for (int i = (ks ? 0 : 2); i < 16; i += 2) mx = fmaxf(fmaxf(mx, S[ks][i]), S[ks][i + 1]);
;   mx = fmaxf(mx, __shfl_xor(mx, 32));
;   if (MODE == 2) mx = selbit ? mx : -1e30f;
;   const float mn = fmaxf(m, mx);
;   if (__any((mn - m) * c2 > 8.f)) {
;     const float alpha = __builtin_amdgcn_exp2f((m - mn) * c2);
;     m = mn;
;     l *= alpha;
; #pragma unroll
;     for (int d = 0; d < DV / 32; ++d) O[d] = O[d] * alpha;
;   }
.LBB0_485:
	s_or_b64 exec, exec, s[12:13]
	v_max_f32_e32 v104, v51, v51
	v_max_f32_e32 v117, v50, v50
	v_max_f32_e32 v104, v117, v104
	v_max3_f32 v104, v104, v52, v53
	v_max3_f32 v104, v104, v54, v55
	v_max3_f32 v104, v104, v56, v57
	v_max3_f32 v104, v104, v58, v59
	v_max3_f32 v104, v104, v60, v61
	v_max3_f32 v104, v104, v62, v63
	v_max3_f32 v104, v104, v64, v65
	v_max3_f32 v104, v104, v34, v35
	v_max3_f32 v104, v104, v36, v37
	v_max3_f32 v104, v104, v38, v39
	v_max3_f32 v104, v104, v40, v41
	v_max3_f32 v104, v104, v42, v43
	v_max3_f32 v104, v104, v44, v45
	v_max3_f32 v104, v104, v46, v47
	v_max3_f32 v104, v104, v48, v49
	ds_bpermute_b32 v117, v165, v104
	ds_read2_b64 v[216:219], v131 offset0:128 offset1:130
	ds_read2_b64 v[220:223], v130 offset0:192 offset1:194
	ds_read2_b64 v[224:227], v131 offset0:132 offset1:134
	ds_read2_b64 v[228:231], v130 offset0:196 offset1:198
	ds_read2_b64 v[232:235], v131 offset0:136 offset1:138
	ds_read2_b64 v[236:239], v130 offset0:200 offset1:202
	ds_read2_b64 v[240:243], v131 offset0:140 offset1:142
	ds_read2_b64 v[244:247], v130 offset0:204 offset1:206
	s_waitcnt lgkmcnt(8)
	v_max3_f32 v104, v116, v104, v117
	v_sub_f32_e32 v117, v104, v116
	v_mul_f32_e32 v117, 0x3e16c740, v117
	v_cmp_lt_f32_e32 vcc, s51, v117
	s_cbranch_vccz .LBB0_502
	v_sub_f32_e32 v116, v116, v104
	v_mul_f32_e32 v116, 0x3e16c740, v116
	v_exp_f32_e32 v116, v116
	s_nop 0
	v_mul_f32_e32 v109, v109, v116
	v_pk_mul_f32 v[16:17], v[16:17], v[116:117] op_sel_hi:[1,0]
	v_pk_mul_f32 v[14:15], v[14:15], v[116:117] op_sel_hi:[1,0]
	v_pk_mul_f32 v[12:13], v[12:13], v[116:117] op_sel_hi:[1,0]
	v_pk_mul_f32 v[10:11], v[10:11], v[116:117] op_sel_hi:[1,0]
	v_pk_mul_f32 v[8:9], v[8:9], v[116:117] op_sel_hi:[1,0]
	v_pk_mul_f32 v[6:7], v[6:7], v[116:117] op_sel_hi:[1,0]
	v_pk_mul_f32 v[4:5], v[4:5], v[116:117] op_sel_hi:[1,0]
	v_pk_mul_f32 v[2:3], v[2:3], v[116:117] op_sel_hi:[1,0]
	v_pk_mul_f32 v[32:33], v[32:33], v[116:117] op_sel_hi:[1,0]
	v_pk_mul_f32 v[30:31], v[30:31], v[116:117] op_sel_hi:[1,0]
	v_pk_mul_f32 v[28:29], v[28:29], v[116:117] op_sel_hi:[1,0]
	v_pk_mul_f32 v[26:27], v[26:27], v[116:117] op_sel_hi:[1,0]
	v_pk_mul_f32 v[24:25], v[24:25], v[116:117] op_sel_hi:[1,0]
	v_pk_mul_f32 v[22:23], v[22:23], v[116:117] op_sel_hi:[1,0]
	v_pk_mul_f32 v[20:21], v[20:21], v[116:117] op_sel_hi:[1,0]
	v_pk_mul_f32 v[18:19], v[18:19], v[116:117] op_sel_hi:[1,0]
	v_mov_b32_e32 v116, v104

; #define MFMA(a, b, c) __builtin_amdgcn_mfma_f32_32x32x16_bf16((a), (b), (c), 0, 0, 0)
; DI int crow(int i, int h) { return (i & 3) + 8 * (i >> 2) + 4 * h; }
; template <int DK, int DV, int MODE>
; DI void fa_qk(f32x16 (&S)[2], const bf16x8 (&q)[DK / 16], const char* base, int lr, int lh) {
;   using C = FA<DK, DV>;
; #pragma unroll
;   for (int ks = 0; ks < 2; ++ks) {
; #pragma unroll
;     for (int kk = 0; kk < DK / 16; ++kk) {
;       const bf16x8 kf = *(const bf16x8*)(base + (ks * 32 + lr) * C::KSTR + (kk * 2 + lh) * 16);
;       if (kk == 0) {
; #pragma unroll
;         for (int i = 0; i < 16; ++i) S[ks][i] = 0.f;
;       }
;       S[ks] = MFMA(kf, q[kk], S[ks]);
;     }
;   }
; }
;   using C = FA<DK, DV>;
;   bool selbit = true;
;   bool need_mask = false;
;   if (MODE != 0) need_mask = (kb * 64 + 63 > wave_qmax - 31);
;   if (MODE == 2) selbit = (sel >> kb) & 1ull;
;   if (MODE == 3) need_mask = need_mask || (kb * 64 <= wave_qmax - 512);
;   const float c2 = scale * 1.4426950408889634f;
;   if (need_mask) {
; #pragma unroll
;     for (int ks = 0; ks < 2; ++ks)
; #pragma unroll
;       for (int i = 0; i < 16; ++i) {
;         const int key = kb * 64 + ks * 32 + crow(i, lh);
;         bool valid = key <= qpos;
;         if (MODE == 2) valid = valid && selbit;
;         if (MODE == 3) valid = valid && (qpos - key < 512);
;         S[ks][i] = valid ? S[ks][i] : -1e30f;
;       }
.LBB0_499:
	v_cmp_le_i32_e32 vcc, s21, v110
	s_and_saveexec_b64 s[10:11], vcc
	s_cbranch_execz .LBB0_488
	s_add_i32 s6, s6, 0
	v_add3_u32 v104, s6, v112, v111
	ds_read_b128 v[34:37], v104
	ds_read_b128 v[38:41], v104 offset:32
	ds_read_b128 v[42:45], v104 offset:64
	ds_read_b128 v[46:49], v104 offset:96
	ds_read_b128 v[118:121], v104 offset:128
	ds_read_b128 v[122:125], v104 offset:160
	ds_read_b128 v[216:219], v104 offset:6656
	ds_read_b128 v[220:223], v104 offset:6688
	ds_read_b128 v[224:227], v104 offset:6720
	ds_read_b128 v[228:231], v104 offset:6752
	ds_read_b128 v[232:235], v104 offset:6784
	ds_read_b128 v[236:239], v104 offset:6816
	s_add_i32 s7, s21, 63
	v_cmp_gt_i32_e64 s[8:9], s7, v106
	v_add3_u32 v130, s6, v114, v115
	v_add_u32_e32 v131, 0x3000, v130
	v_add_u32_e32 v130, 0x4000, v130
	s_waitcnt lgkmcnt(11)
	v_mfma_f32_32x32x16_bf16 v[50:65], v[34:37], v[82:85], 0
	s_waitcnt lgkmcnt(10)
	v_mfma_f32_32x32x16_bf16 v[50:65], v[38:41], v[66:69], v[50:65]
	s_waitcnt lgkmcnt(9)
	v_mfma_f32_32x32x16_bf16 v[50:65], v[42:45], v[70:73], v[50:65]
	s_waitcnt lgkmcnt(8)
	v_mfma_f32_32x32x16_bf16 v[50:65], v[46:49], v[74:77], v[50:65]
	s_waitcnt lgkmcnt(7)
	v_mfma_f32_32x32x16_bf16 v[50:65], v[118:121], v[78:81], v[50:65]
	s_waitcnt lgkmcnt(6)
	v_mfma_f32_32x32x16_bf16 v[50:65], v[122:125], v[86:89], v[50:65]
	s_waitcnt lgkmcnt(5)
	v_mfma_f32_32x32x16_bf16 v[34:49], v[216:219], v[82:85], 0
	s_waitcnt lgkmcnt(4)
	v_mfma_f32_32x32x16_bf16 v[34:49], v[220:223], v[66:69], v[34:49]
	s_waitcnt lgkmcnt(3)
	v_mfma_f32_32x32x16_bf16 v[34:49], v[224:227], v[70:73], v[34:49]
	s_waitcnt lgkmcnt(2)
	v_mfma_f32_32x32x16_bf16 v[34:49], v[228:231], v[74:77], v[34:49]
	s_waitcnt lgkmcnt(1)
	v_mfma_f32_32x32x16_bf16 v[34:49], v[232:235], v[78:81], v[34:49]
	s_waitcnt lgkmcnt(0)
	v_mfma_f32_32x32x16_bf16 v[34:49], v[236:239], v[86:89], v[34:49]
	s_and_saveexec_b64 s[12:13], s[8:9]
	s_cbranch_execz .LBB0_485
	v_add_u32_e32 v104, s21, v113
	v_cmp_le_i32_e32 vcc, v104, v92
	v_add_u32_e32 v117, 2, v104
	s_nop 0
	v_cndmask_b32_e32 v50, v208, v50, vcc
	v_cmp_lt_i32_e32 vcc, v104, v92
	s_nop 1
	v_cndmask_b32_e32 v51, v208, v51, vcc
	v_cmp_le_i32_e32 vcc, v117, v92
	v_add_u32_e32 v117, 3, v104
	s_nop 0
	v_cndmask_b32_e32 v52, v208, v52, vcc
	v_cmp_le_i32_e32 vcc, v117, v92
	v_add_u32_e32 v117, 8, v104
	s_nop 0
	v_cndmask_b32_e32 v53, v208, v53, vcc
	v_cmp_le_i32_e32 vcc, v117, v92
	v_add_u32_e32 v117, 9, v104
	s_nop 0
	v_cndmask_b32_e32 v54, v208, v54, vcc
	v_cmp_le_i32_e32 vcc, v117, v92
	v_add_u32_e32 v117, 10, v104
	s_nop 0
	v_cndmask_b32_e32 v55, v208, v55, vcc
	v_cmp_le_i32_e32 vcc, v117, v92
	v_add_u32_e32 v117, 11, v104
	s_nop 0
	v_cndmask_b32_e32 v56, v208, v56, vcc
	v_cmp_le_i32_e32 vcc, v117, v92
	v_add_u32_e32 v117, 16, v104
	s_nop 0
	v_cndmask_b32_e32 v57, v208, v57, vcc
	v_cmp_le_i32_e32 vcc, v117, v92
	v_add_u32_e32 v117, 17, v104
	s_nop 0
	v_cndmask_b32_e32 v58, v208, v58, vcc
	v_cmp_le_i32_e32 vcc, v117, v92
	v_add_u32_e32 v117, 18, v104
	s_nop 0
	v_cndmask_b32_e32 v59, v208, v59, vcc
	v_cmp_le_i32_e32 vcc, v117, v92
	v_add_u32_e32 v117, 19, v104
	s_nop 0
	v_cndmask_b32_e32 v60, v208, v60, vcc
	v_cmp_le_i32_e32 vcc, v117, v92
	v_add_u32_e32 v117, 24, v104
	s_nop 0
	v_cndmask_b32_e32 v61, v208, v61, vcc
	v_cmp_le_i32_e32 vcc, v117, v92
	v_add_u32_e32 v117, 25, v104
	s_nop 0
	v_cndmask_b32_e32 v62, v208, v62, vcc
	v_cmp_le_i32_e32 vcc, v117, v92
	v_add_u32_e32 v117, 26, v104
	s_nop 0
	v_cndmask_b32_e32 v63, v208, v63, vcc
	v_cmp_le_i32_e32 vcc, v117, v92
	v_add_u32_e32 v117, 27, v104
	s_nop 0
	v_cndmask_b32_e32 v64, v208, v64, vcc
	v_cmp_le_i32_e32 vcc, v117, v92
	v_add_u32_e32 v117, 32, v104
	s_nop 0
	v_cndmask_b32_e32 v65, v208, v65, vcc
	v_cmp_le_i32_e32 vcc, v117, v92
	v_add_u32_e32 v117, 33, v104
	s_nop 0
	v_cndmask_b32_e32 v34, v208, v34, vcc
	v_cmp_le_i32_e32 vcc, v117, v92
	v_add_u32_e32 v117, 34, v104
	s_nop 0
	v_cndmask_b32_e32 v35, v208, v35, vcc
	v_cmp_le_i32_e32 vcc, v117, v92
	v_add_u32_e32 v117, 35, v104
	s_nop 0
	v_cndmask_b32_e32 v36, v208, v36, vcc
	v_cmp_le_i32_e32 vcc, v117, v92
	v_add_u32_e32 v117, 40, v104
	s_nop 0
	v_cndmask_b32_e32 v37, v208, v37, vcc
	v_cmp_le_i32_e32 vcc, v117, v92
	v_add_u32_e32 v117, 41, v104
	s_nop 0
	v_cndmask_b32_e32 v38, v208, v38, vcc
	v_cmp_le_i32_e32 vcc, v117, v92
	v_add_u32_e32 v117, 42, v104
	s_nop 0
	v_cndmask_b32_e32 v39, v208, v39, vcc
	v_cmp_le_i32_e32 vcc, v117, v92
	v_add_u32_e32 v117, 43, v104
	s_nop 0
	v_cndmask_b32_e32 v40, v208, v40, vcc
	v_cmp_le_i32_e32 vcc, v117, v92
	v_add_u32_e32 v117, 48, v104
	s_nop 0
	v_cndmask_b32_e32 v41, v208, v41, vcc
	v_cmp_le_i32_e32 vcc, v117, v92
	v_add_u32_e32 v117, 49, v104
	s_nop 0
	v_cndmask_b32_e32 v42, v208, v42, vcc
	v_cmp_le_i32_e32 vcc, v117, v92
	v_add_u32_e32 v117, 50, v104
	s_nop 0
	v_cndmask_b32_e32 v43, v208, v43, vcc
	v_cmp_le_i32_e32 vcc, v117, v92
	v_add_u32_e32 v117, 51, v104
	s_nop 0
	v_cndmask_b32_e32 v44, v208, v44, vcc
	v_cmp_le_i32_e32 vcc, v117, v92
	v_add_u32_e32 v117, 56, v104
	s_nop 0
	v_cndmask_b32_e32 v45, v208, v45, vcc
	v_cmp_le_i32_e32 vcc, v117, v92
	v_add_u32_e32 v117, 57, v104
	s_nop 0
	v_cndmask_b32_e32 v46, v208, v46, vcc
	v_cmp_le_i32_e32 vcc, v117, v92
	v_add_u32_e32 v117, 58, v104
	v_add_u32_e32 v104, 59, v104
	v_cndmask_b32_e32 v47, v208, v47, vcc
	v_cmp_le_i32_e32 vcc, v117, v92
	s_nop 1
	v_cndmask_b32_e32 v48, v208, v48, vcc
	v_cmp_le_i32_e32 vcc, v104, v92
	s_nop 1
	v_cndmask_b32_e32 v49, v208, v49, vcc
	s_branch .LBB0_485

; #define MFMA(a, b, c) __builtin_amdgcn_mfma_f32_32x32x16_bf16((a), (b), (c), 0, 0, 0)
; DI int crow(int i, int h) { return (i & 3) + 8 * (i >> 2) + 4 * h; }
; template <int DK, int DV, int MODE>
; DI bool fa_active(int kb, int wave_qmax, unsigned long long sel) {
;   bool active = true;
;   if (MODE != 0) active = (kb * 64 <= wave_qmax);
;   if (MODE == 2) {
;     const bool selbit = (sel >> kb) & 1ull;
;     if (__ballot(selbit) == 0ull) active = false;
;   }
;   return active;
; }
; template <int DK, int DV, int MODE>
; DI void fa_qk(f32x16 (&S)[2], const bf16x8 (&q)[DK / 16], const char* base, int lr, int lh) {
;   using C = FA<DK, DV>;
; #pragma unroll
;   for (int ks = 0; ks < 2; ++ks) {
; #pragma unroll
;     for (int kk = 0; kk < DK / 16; ++kk) {
;       const bf16x8 kf = *(const bf16x8*)(base + (ks * 32 + lr) * C::KSTR + (kk * 2 + lh) * 16);
;       if (kk == 0) {
; #pragma unroll
;         for (int i = 0; i < 16; ++i) S[ks][i] = 0.f;
;       }
;       S[ks] = MFMA(kf, q[kk], S[ks]);
;     }
;   }
; }
;   using C = FA<DK, DV>;
;   bool selbit = true;
;   bool need_mask = false;
;   if (MODE != 0) need_mask = (kb * 64 + 63 > wave_qmax - 31);
;   if (MODE == 2) selbit = (sel >> kb) & 1ull;
;   if (MODE == 3) need_mask = need_mask || (kb * 64 <= wave_qmax - 512);
;   const float c2 = scale * 1.4426950408889634f;
;   if (need_mask) {
; #pragma unroll
;     for (int ks = 0; ks < 2; ++ks)
; #pragma unroll
;       for (int i = 0; i < 16; ++i) {
;         const int key = kb * 64 + ks * 32 + crow(i, lh);
;         bool valid = key <= qpos;
;         if (MODE == 2) valid = valid && selbit;
;         if (MODE == 3) valid = valid && (qpos - key < 512);
;         S[ks][i] = valid ? S[ks][i] : -1e30f;
;       }
.LBB0_561:
	v_lshrrev_b64 v[80:81], s0, v[2:3]
	s_sub_i32 s8, s7, 63
	v_and_b32_e32 v14, 1, v80
	s_cmp_le_u32 s8, s20
	v_cmp_ne_u32_e32 vcc, 0, v14
	s_cselect_b64 s[8:9], -1, 0
	s_cmp_lg_u64 vcc, 0
	s_cselect_b64 s[10:11], -1, 0
	s_and_b64 s[8:9], s[10:11], s[8:9]
	s_andn2_b64 vcc, exec, s[8:9]
	v_cmp_eq_u32_e64 s[10:11], 1, v14
	s_cbranch_vccnz .LBB0_550
	s_add_i32 s6, s6, 0
	v_add3_u32 v14, s6, v115, v114
	ds_read_b128 v[216:219], v14
	ds_read_b128 v[220:223], v14 offset:32
	ds_read_b128 v[224:227], v14 offset:64
	ds_read_b128 v[228:231], v14 offset:96
	ds_read_b128 v[232:235], v14 offset:4608
	ds_read_b128 v[236:239], v14 offset:4640
	ds_read_b128 v[240:243], v14 offset:4672
	ds_read_b128 v[244:247], v14 offset:4704
	s_cmp_gt_u32 s7, s35
	s_cselect_b64 s[8:9], -1, 0
	s_cmp_le_u32 s7, s35
	s_waitcnt lgkmcnt(7)
	v_mfma_f32_32x32x16_bf16 v[96:111], v[216:219], v[152:155], 0
	s_waitcnt lgkmcnt(6)
	v_mfma_f32_32x32x16_bf16 v[96:111], v[220:223], v[144:147], v[96:111]
	s_waitcnt lgkmcnt(5)
	v_mfma_f32_32x32x16_bf16 v[96:111], v[224:227], v[148:151], v[96:111]
	s_waitcnt lgkmcnt(4)
	v_mfma_f32_32x32x16_bf16 v[96:111], v[228:231], v[156:159], v[96:111]
	s_waitcnt lgkmcnt(3)
	v_mfma_f32_32x32x16_bf16 v[80:95], v[232:235], v[152:155], 0
	s_waitcnt lgkmcnt(2)
	v_mfma_f32_32x32x16_bf16 v[80:95], v[236:239], v[144:147], v[80:95]
	s_waitcnt lgkmcnt(1)
	v_mfma_f32_32x32x16_bf16 v[80:95], v[240:243], v[148:151], v[80:95]
	s_waitcnt lgkmcnt(0)
	v_mfma_f32_32x32x16_bf16 v[80:95], v[244:247], v[156:159], v[80:95]
	v_add3_u32 v247, s6, v117, v115
	v_add_u32_e32 v243, 0x2000, v247
	v_add_u32_e32 v247, 0x3000, v247
	s_cbranch_scc1 .LBB0_564
	v_add_u32_e32 v14, s7, v116
	v_subrev_u32_e32 v119, 63, v14
	v_cmp_le_i32_e32 vcc, v119, v162
	s_and_b64 vcc, vcc, s[10:11]
	s_nop 0
	v_cndmask_b32_e32 v96, v208, v96, vcc
	v_cmp_lt_i32_e32 vcc, v119, v162
	s_and_b64 vcc, vcc, s[10:11]
	v_subrev_u32_e32 v119, 61, v14
	v_cndmask_b32_e32 v97, v208, v97, vcc
	v_cmp_le_i32_e32 vcc, v119, v162
	s_and_b64 vcc, vcc, s[10:11]
	v_subrev_u32_e32 v119, 60, v14
	v_cndmask_b32_e32 v98, v208, v98, vcc
	v_cmp_le_i32_e32 vcc, v119, v162
	s_and_b64 vcc, vcc, s[10:11]
	v_subrev_u32_e32 v119, 55, v14
	v_cndmask_b32_e32 v99, v208, v99, vcc
	v_cmp_le_i32_e32 vcc, v119, v162
	s_and_b64 vcc, vcc, s[10:11]
	v_subrev_u32_e32 v119, 54, v14
	v_cndmask_b32_e32 v100, v208, v100, vcc
	v_cmp_le_i32_e32 vcc, v119, v162
	s_and_b64 vcc, vcc, s[10:11]
	v_subrev_u32_e32 v119, 53, v14
	v_cndmask_b32_e32 v101, v208, v101, vcc
	v_cmp_le_i32_e32 vcc, v119, v162
	s_and_b64 vcc, vcc, s[10:11]
	v_subrev_u32_e32 v119, 52, v14
	v_cndmask_b32_e32 v102, v208, v102, vcc
	v_cmp_le_i32_e32 vcc, v119, v162
	s_and_b64 vcc, vcc, s[10:11]
	v_subrev_u32_e32 v119, 47, v14
	v_cndmask_b32_e32 v103, v208, v103, vcc
	v_cmp_le_i32_e32 vcc, v119, v162
	s_and_b64 vcc, vcc, s[10:11]
	v_subrev_u32_e32 v119, 46, v14
	v_cndmask_b32_e32 v104, v208, v104, vcc
	v_cmp_le_i32_e32 vcc, v119, v162
	s_and_b64 vcc, vcc, s[10:11]
	v_subrev_u32_e32 v119, 45, v14
	v_cndmask_b32_e32 v105, v208, v105, vcc
	v_cmp_le_i32_e32 vcc, v119, v162
	s_and_b64 vcc, vcc, s[10:11]
	v_subrev_u32_e32 v119, 44, v14
	v_cndmask_b32_e32 v106, v208, v106, vcc
	v_cmp_le_i32_e32 vcc, v119, v162
	s_and_b64 vcc, vcc, s[10:11]
	v_subrev_u32_e32 v119, 39, v14
	v_cndmask_b32_e32 v107, v208, v107, vcc
	v_cmp_le_i32_e32 vcc, v119, v162
	s_and_b64 vcc, vcc, s[10:11]
	v_subrev_u32_e32 v119, 38, v14
	v_cndmask_b32_e32 v108, v208, v108, vcc
	v_cmp_le_i32_e32 vcc, v119, v162
	s_and_b64 vcc, vcc, s[10:11]
	v_subrev_u32_e32 v119, 37, v14
	v_cndmask_b32_e32 v109, v208, v109, vcc
	v_cmp_le_i32_e32 vcc, v119, v162
	s_and_b64 vcc, vcc, s[10:11]
	v_subrev_u32_e32 v119, 36, v14
	v_cndmask_b32_e32 v110, v208, v110, vcc
	v_cmp_le_i32_e32 vcc, v119, v162
	s_and_b64 vcc, vcc, s[10:11]
	v_subrev_u32_e32 v119, 31, v14
	v_cndmask_b32_e32 v111, v208, v111, vcc
	v_cmp_le_i32_e32 vcc, v119, v162
	s_and_b64 vcc, vcc, s[10:11]
	v_subrev_u32_e32 v119, 30, v14
	v_cndmask_b32_e32 v80, v208, v80, vcc
	v_cmp_le_i32_e32 vcc, v119, v162
	s_and_b64 vcc, vcc, s[10:11]
	v_subrev_u32_e32 v119, 29, v14
	v_cndmask_b32_e32 v81, v208, v81, vcc
	v_cmp_le_i32_e32 vcc, v119, v162
	s_and_b64 vcc, vcc, s[10:11]
	v_subrev_u32_e32 v119, 28, v14
	v_cndmask_b32_e32 v82, v208, v82, vcc
	v_cmp_le_i32_e32 vcc, v119, v162
	s_and_b64 vcc, vcc, s[10:11]
	v_subrev_u32_e32 v119, 23, v14
	v_cndmask_b32_e32 v83, v208, v83, vcc
	v_cmp_le_i32_e32 vcc, v119, v162
	s_and_b64 vcc, vcc, s[10:11]
	v_subrev_u32_e32 v119, 22, v14
	v_cndmask_b32_e32 v84, v208, v84, vcc
	v_cmp_le_i32_e32 vcc, v119, v162
	s_and_b64 vcc, vcc, s[10:11]
	v_subrev_u32_e32 v119, 21, v14
	v_cndmask_b32_e32 v85, v208, v85, vcc
	v_cmp_le_i32_e32 vcc, v119, v162
	s_and_b64 vcc, vcc, s[10:11]
	v_subrev_u32_e32 v119, 20, v14
	v_cndmask_b32_e32 v86, v208, v86, vcc
	v_cmp_le_i32_e32 vcc, v119, v162
	s_and_b64 vcc, vcc, s[10:11]
	v_add_u32_e32 v119, -15, v14
	v_cndmask_b32_e32 v87, v208, v87, vcc
	v_cmp_le_i32_e32 vcc, v119, v162
	s_and_b64 vcc, vcc, s[10:11]
	v_add_u32_e32 v119, -14, v14
	v_cndmask_b32_e32 v88, v208, v88, vcc
	v_cmp_le_i32_e32 vcc, v119, v162
	s_and_b64 vcc, vcc, s[10:11]
	v_add_u32_e32 v119, -13, v14
	v_cndmask_b32_e32 v89, v208, v89, vcc
	v_cmp_le_i32_e32 vcc, v119, v162
	s_and_b64 vcc, vcc, s[10:11]
	v_add_u32_e32 v119, -12, v14
	v_cndmask_b32_e32 v90, v208, v90, vcc
	v_cmp_le_i32_e32 vcc, v119, v162
	s_and_b64 vcc, vcc, s[10:11]
	v_add_u32_e32 v119, -7, v14
	v_cndmask_b32_e32 v91, v208, v91, vcc
	v_cmp_le_i32_e32 vcc, v119, v162
	s_and_b64 vcc, vcc, s[10:11]
	v_add_u32_e32 v119, -6, v14
	v_cndmask_b32_e32 v92, v208, v92, vcc
	v_cmp_le_i32_e32 vcc, v119, v162
	s_and_b64 vcc, vcc, s[10:11]
	v_add_u32_e32 v119, -5, v14
	v_cndmask_b32_e32 v93, v208, v93, vcc
	v_cmp_le_i32_e32 vcc, v119, v162
	s_and_b64 vcc, vcc, s[10:11]
	v_add_u32_e32 v14, -4, v14
	v_cndmask_b32_e32 v94, v208, v94, vcc
	v_cmp_le_i32_e32 vcc, v14, v162
	s_and_b64 vcc, vcc, s[10:11]
	s_nop 0
	v_cndmask_b32_e32 v95, v208, v95, vcc
;     ...
;   float mx = fmaxf(S[0][0], S[0][1]);
; #pragma unroll
;   for (int ks = 0; ks < 2; ++ks)
; #pragma unroll
;     for (int i = (ks ? 0 : 2); i < 16; i += 2) mx = fmaxf(fmaxf(mx, S[ks][i]), S[ks][i + 1]);
;   mx = fmaxf(mx, __shfl_xor(mx, 32));
;   if (MODE == 2) mx = selbit ? mx : -1e30f;
;   const float mn = fmaxf(m, mx);
;   if (__any((mn - m) * c2 > 8.f)) {
.LBB0_564:
	s_nop 0
	v_max_f32_e32 v14, v97, v97
	v_max_f32_e32 v119, v96, v96
	v_max_f32_e32 v14, v119, v14
	v_max3_f32 v14, v14, v98, v99
	v_max3_f32 v14, v14, v100, v101
	v_max3_f32 v14, v14, v102, v103
	v_max3_f32 v14, v14, v104, v105
	v_max3_f32 v14, v14, v106, v107
	v_max3_f32 v14, v14, v108, v109
	v_max3_f32 v14, v14, v110, v111
	v_max3_f32 v14, v14, v80, v81
	v_max3_f32 v14, v14, v82, v83
	v_max3_f32 v14, v14, v84, v85
	v_max3_f32 v14, v14, v86, v87
	v_max3_f32 v14, v14, v88, v89
	v_max3_f32 v14, v14, v90, v91
	v_max3_f32 v14, v14, v92, v93
	v_max3_f32 v14, v14, v94, v95
	ds_bpermute_b32 v119, v165, v14
	ds_read2_b64 v[216:219], v243 offset0:128 offset1:130
	ds_read2_b64 v[220:223], v247 offset0:192 offset1:194
	ds_read2_b64 v[224:227], v243 offset0:132 offset1:134
	ds_read2_b64 v[228:231], v247 offset0:196 offset1:198
	ds_read2_b64 v[232:235], v243 offset0:136 offset1:138
	ds_read2_b64 v[236:239], v247 offset0:200 offset1:202
	ds_read2_b64 v[240:243], v243 offset0:140 offset1:142
	ds_read2_b64 v[244:247], v247 offset0:204 offset1:206
	s_waitcnt lgkmcnt(8)
	v_max_f32_e32 v119, v119, v119
	v_max_f32_e32 v14, v14, v119
	v_cndmask_b32_e64 v14, v208, v14, s[10:11]
	v_max_f32_e32 v119, v118, v118
	v_max_f32_e32 v14, v119, v14
	v_sub_f32_e32 v119, v14, v118
	v_mul_f32_e32 v119, 0x3e38aa3b, v119
	v_cmp_lt_f32_e32 vcc, s51, v119
	s_cbranch_vccnz .LBB0_548
	v_mov_b32_e32 v14, v118
	s_branch .LBB0_549

; #define MFMA(a, b, c) __builtin_amdgcn_mfma_f32_32x32x16_bf16((a), (b), (c), 0, 0, 0)
; DI int crow(int i, int h) { return (i & 3) + 8 * (i >> 2) + 4 * h; }
; template <int DK, int DV, int MODE>
; DI void fa_qk(f32x16 (&S)[2], const bf16x8 (&q)[DK / 16], const char* base, int lr, int lh) {
;   using C = FA<DK, DV>;
; #pragma unroll
;   for (int ks = 0; ks < 2; ++ks) {
; #pragma unroll
;     for (int kk = 0; kk < DK / 16; ++kk) {
;       const bf16x8 kf = *(const bf16x8*)(base + (ks * 32 + lr) * C::KSTR + (kk * 2 + lh) * 16);
;       if (kk == 0) {
; #pragma unroll
;         for (int i = 0; i < 16; ++i) S[ks][i] = 0.f;
;       }
;       S[ks] = MFMA(kf, q[kk], S[ks]);
;     }
;   }
; }
;   using C = FA<DK, DV>;
;   bool selbit = true;
;   bool need_mask = false;
;   if (MODE != 0) need_mask = (kb * 64 + 63 > wave_qmax - 31);
;   if (MODE == 2) selbit = (sel >> kb) & 1ull;
;   if (MODE == 3) need_mask = need_mask || (kb * 64 <= wave_qmax - 512);
;   const float c2 = scale * 1.4426950408889634f;
;   if (need_mask) {
; #pragma unroll
;     for (int ks = 0; ks < 2; ++ks)
; #pragma unroll
;       for (int i = 0; i < 16; ++i) {
;         const int key = kb * 64 + ks * 32 + crow(i, lh);
;         bool valid = key <= qpos;
;         if (MODE == 2) valid = valid && selbit;
;         if (MODE == 3) valid = valid && (qpos - key < 512);
;         S[ks][i] = valid ? S[ks][i] : -1e30f;
;       }
.LBB0_597:
	s_cmp_gt_i32 s7, s20
	s_cbranch_scc1 .LBB0_586
	s_add_i32 s0, s0, 0
	v_add3_u32 v12, s0, v172, v171
	ds_read_b128 v[216:219], v12
	ds_read_b128 v[220:223], v12 offset:32
	ds_read_b128 v[224:227], v12 offset:64
	ds_read_b128 v[228:231], v12 offset:96
	ds_read_b128 v[232:235], v12 offset:4608
	ds_read_b128 v[236:239], v12 offset:4640
	ds_read_b128 v[240:243], v12 offset:4672
	ds_read_b128 v[244:247], v12 offset:4704
	s_add_i32 s1, s7, 31
	s_cmp_gt_i32 s1, s43
	s_cselect_b64 s[8:9], -1, 0
	s_cmp_le_i32 s7, s19
	s_cselect_b64 s[10:11], -1, 0
	s_or_b64 s[8:9], s[8:9], s[10:11]
	s_andn2_b64 vcc, exec, s[8:9]
	s_waitcnt lgkmcnt(7)
	v_mfma_f32_32x32x16_bf16 v[128:143], v[216:219], v[152:155], 0
	s_waitcnt lgkmcnt(6)
	v_mfma_f32_32x32x16_bf16 v[128:143], v[220:223], v[144:147], v[128:143]
	s_waitcnt lgkmcnt(5)
	v_mfma_f32_32x32x16_bf16 v[128:143], v[224:227], v[148:151], v[128:143]
	s_waitcnt lgkmcnt(4)
	v_mfma_f32_32x32x16_bf16 v[128:143], v[228:231], v[156:159], v[128:143]
	s_waitcnt lgkmcnt(3)
	v_mfma_f32_32x32x16_bf16 v[112:127], v[232:235], v[152:155], 0
	s_waitcnt lgkmcnt(2)
	v_mfma_f32_32x32x16_bf16 v[112:127], v[236:239], v[144:147], v[112:127]
	s_waitcnt lgkmcnt(1)
	v_mfma_f32_32x32x16_bf16 v[112:127], v[240:243], v[148:151], v[112:127]
	s_waitcnt lgkmcnt(0)
	v_mfma_f32_32x32x16_bf16 v[112:127], v[244:247], v[156:159], v[112:127]
	v_add3_u32 v247, s0, v175, v172
	v_add_u32_e32 v243, 0x2000, v247
	v_add_u32_e32 v247, 0x3000, v247
	s_cbranch_vccnz .LBB0_600
	v_add_u32_e32 v12, s7, v173
	v_cmp_le_i32_e32 vcc, v12, v162
	v_cmp_gt_i32_e64 s[10:11], v12, v174
	s_and_b64 vcc, vcc, s[10:11]
	v_cndmask_b32_e32 v128, v208, v128, vcc
	v_cmp_lt_i32_e32 vcc, v12, v162
	v_cmp_ge_i32_e64 s[10:11], v12, v174
	s_and_b64 vcc, vcc, s[10:11]
	v_add_u32_e32 v176, 2, v12
	v_cndmask_b32_e32 v129, v208, v129, vcc
	v_cmp_le_i32_e32 vcc, v176, v162
	v_cmp_gt_i32_e64 s[10:11], v176, v174
	s_and_b64 vcc, vcc, s[10:11]
	v_add_u32_e32 v176, 3, v12
	v_cndmask_b32_e32 v130, v208, v130, vcc
	v_cmp_le_i32_e32 vcc, v176, v162
	v_cmp_gt_i32_e64 s[10:11], v176, v174
	s_and_b64 vcc, vcc, s[10:11]
	v_add_u32_e32 v176, 8, v12
	v_cndmask_b32_e32 v131, v208, v131, vcc
	v_cmp_le_i32_e32 vcc, v176, v162
	v_cmp_gt_i32_e64 s[10:11], v176, v174
	s_and_b64 vcc, vcc, s[10:11]
	v_add_u32_e32 v176, 9, v12
	v_cndmask_b32_e32 v132, v208, v132, vcc
	v_cmp_le_i32_e32 vcc, v176, v162
	v_cmp_gt_i32_e64 s[10:11], v176, v174
	s_and_b64 vcc, vcc, s[10:11]
	v_add_u32_e32 v176, 10, v12
	v_cndmask_b32_e32 v133, v208, v133, vcc
	v_cmp_le_i32_e32 vcc, v176, v162
	v_cmp_gt_i32_e64 s[10:11], v176, v174
	s_and_b64 vcc, vcc, s[10:11]
	v_add_u32_e32 v176, 11, v12
	v_cndmask_b32_e32 v134, v208, v134, vcc
	v_cmp_le_i32_e32 vcc, v176, v162
	v_cmp_gt_i32_e64 s[10:11], v176, v174
	s_and_b64 vcc, vcc, s[10:11]
	v_add_u32_e32 v176, 16, v12
	v_cndmask_b32_e32 v135, v208, v135, vcc
	v_cmp_le_i32_e32 vcc, v176, v162
	v_cmp_gt_i32_e64 s[10:11], v176, v174
	s_and_b64 vcc, vcc, s[10:11]
	v_add_u32_e32 v176, 17, v12
	v_cndmask_b32_e32 v136, v208, v136, vcc
	v_cmp_le_i32_e32 vcc, v176, v162
	v_cmp_gt_i32_e64 s[10:11], v176, v174
	s_and_b64 vcc, vcc, s[10:11]
	v_add_u32_e32 v176, 18, v12
	v_cndmask_b32_e32 v137, v208, v137, vcc
	v_cmp_le_i32_e32 vcc, v176, v162
	v_cmp_gt_i32_e64 s[10:11], v176, v174
	s_and_b64 vcc, vcc, s[10:11]
	v_add_u32_e32 v176, 19, v12
	v_cndmask_b32_e32 v138, v208, v138, vcc
	v_cmp_le_i32_e32 vcc, v176, v162
	v_cmp_gt_i32_e64 s[10:11], v176, v174
	s_and_b64 vcc, vcc, s[10:11]
	v_add_u32_e32 v176, 24, v12
	v_cndmask_b32_e32 v139, v208, v139, vcc
	v_cmp_le_i32_e32 vcc, v176, v162
	v_cmp_gt_i32_e64 s[10:11], v176, v174
	s_and_b64 vcc, vcc, s[10:11]
	v_add_u32_e32 v176, 25, v12
	v_cndmask_b32_e32 v140, v208, v140, vcc
	v_cmp_le_i32_e32 vcc, v176, v162
	v_cmp_gt_i32_e64 s[10:11], v176, v174
	s_and_b64 vcc, vcc, s[10:11]
	v_add_u32_e32 v176, 26, v12
	v_cndmask_b32_e32 v141, v208, v141, vcc
	v_cmp_le_i32_e32 vcc, v176, v162
	v_cmp_gt_i32_e64 s[10:11], v176, v174
	s_and_b64 vcc, vcc, s[10:11]
	v_add_u32_e32 v176, 27, v12
	v_cndmask_b32_e32 v142, v208, v142, vcc
	v_cmp_le_i32_e32 vcc, v176, v162
	v_cmp_gt_i32_e64 s[10:11], v176, v174
	s_and_b64 vcc, vcc, s[10:11]
	v_add_u32_e32 v176, 32, v12
	v_cndmask_b32_e32 v143, v208, v143, vcc
	v_cmp_le_i32_e32 vcc, v176, v162
	v_cmp_gt_i32_e64 s[10:11], v176, v174
	s_and_b64 vcc, vcc, s[10:11]
	v_add_u32_e32 v176, 33, v12
	v_cndmask_b32_e32 v112, v208, v112, vcc
	v_cmp_le_i32_e32 vcc, v176, v162
	v_cmp_gt_i32_e64 s[10:11], v176, v174
	s_and_b64 vcc, vcc, s[10:11]
	v_add_u32_e32 v176, 34, v12
	v_cndmask_b32_e32 v113, v208, v113, vcc
	v_cmp_le_i32_e32 vcc, v176, v162
	v_cmp_gt_i32_e64 s[10:11], v176, v174
	s_and_b64 vcc, vcc, s[10:11]
	v_add_u32_e32 v176, 35, v12
	v_cndmask_b32_e32 v114, v208, v114, vcc
	v_cmp_le_i32_e32 vcc, v176, v162
	v_cmp_gt_i32_e64 s[10:11], v176, v174
	s_and_b64 vcc, vcc, s[10:11]
	v_add_u32_e32 v176, 40, v12
	v_cndmask_b32_e32 v115, v208, v115, vcc
	v_cmp_le_i32_e32 vcc, v176, v162
	v_cmp_gt_i32_e64 s[10:11], v176, v174
	s_and_b64 vcc, vcc, s[10:11]
	v_add_u32_e32 v176, 41, v12
	v_cndmask_b32_e32 v116, v208, v116, vcc
	v_cmp_le_i32_e32 vcc, v176, v162
	v_cmp_gt_i32_e64 s[10:11], v176, v174
	s_and_b64 vcc, vcc, s[10:11]
	v_add_u32_e32 v176, 42, v12
	v_cndmask_b32_e32 v117, v208, v117, vcc
	v_cmp_le_i32_e32 vcc, v176, v162
	v_cmp_gt_i32_e64 s[10:11], v176, v174
	s_and_b64 vcc, vcc, s[10:11]
	v_add_u32_e32 v176, 43, v12
	v_cndmask_b32_e32 v118, v208, v118, vcc
	v_cmp_le_i32_e32 vcc, v176, v162
	v_cmp_gt_i32_e64 s[10:11], v176, v174
	s_and_b64 vcc, vcc, s[10:11]
	v_add_u32_e32 v176, 48, v12
	v_cndmask_b32_e32 v119, v208, v119, vcc
	v_cmp_le_i32_e32 vcc, v176, v162
	v_cmp_gt_i32_e64 s[10:11], v176, v174
	s_and_b64 vcc, vcc, s[10:11]
	v_add_u32_e32 v176, 49, v12
	v_cndmask_b32_e32 v120, v208, v120, vcc
	v_cmp_le_i32_e32 vcc, v176, v162
	v_cmp_gt_i32_e64 s[10:11], v176, v174
	s_and_b64 vcc, vcc, s[10:11]
	v_add_u32_e32 v176, 50, v12
	v_cndmask_b32_e32 v121, v208, v121, vcc
	v_cmp_le_i32_e32 vcc, v176, v162
	v_cmp_gt_i32_e64 s[10:11], v176, v174
	s_and_b64 vcc, vcc, s[10:11]
	v_add_u32_e32 v176, 51, v12
	v_cndmask_b32_e32 v122, v208, v122, vcc
	v_cmp_le_i32_e32 vcc, v176, v162
	v_cmp_gt_i32_e64 s[10:11], v176, v174
	s_and_b64 vcc, vcc, s[10:11]
	v_add_u32_e32 v176, 56, v12
	v_cndmask_b32_e32 v123, v208, v123, vcc
	v_cmp_le_i32_e32 vcc, v176, v162
	v_cmp_gt_i32_e64 s[10:11], v176, v174
	s_and_b64 vcc, vcc, s[10:11]
	v_add_u32_e32 v176, 57, v12
	v_cndmask_b32_e32 v124, v208, v124, vcc
	v_cmp_le_i32_e32 vcc, v176, v162
	v_cmp_gt_i32_e64 s[10:11], v176, v174
	s_and_b64 vcc, vcc, s[10:11]
	v_add_u32_e32 v176, 58, v12
	v_cndmask_b32_e32 v125, v208, v125, vcc
	v_cmp_le_i32_e32 vcc, v176, v162
	v_cmp_gt_i32_e64 s[10:11], v176, v174
	s_and_b64 vcc, vcc, s[10:11]
	v_add_u32_e32 v12, 59, v12
	v_cndmask_b32_e32 v126, v208, v126, vcc
	v_cmp_le_i32_e32 vcc, v12, v162
	v_cmp_gt_i32_e64 s[10:11], v12, v174
	s_and_b64 vcc, vcc, s[10:11]
	v_cndmask_b32_e32 v127, v208, v127, vcc
;     ...
;   float mx = fmaxf(S[0][0], S[0][1]);
; #pragma unroll
;   for (int ks = 0; ks < 2; ++ks)
; #pragma unroll
;     for (int i = (ks ? 0 : 2); i < 16; i += 2) mx = fmaxf(fmaxf(mx, S[ks][i]), S[ks][i + 1]);
;   mx = fmaxf(mx, __shfl_xor(mx, 32));
;   if (MODE == 2) mx = selbit ? mx : -1e30f;
;   const float mn = fmaxf(m, mx);
;   if (__any((mn - m) * c2 > 8.f)) {
.LBB0_600:
	s_nop 0
	v_max_f32_e32 v12, v129, v129
	v_max_f32_e32 v176, v128, v128
	v_max_f32_e32 v12, v176, v12
	v_max3_f32 v12, v12, v130, v131
	v_max3_f32 v12, v12, v132, v133
	v_max3_f32 v12, v12, v134, v135
	v_max3_f32 v12, v12, v136, v137
	v_max3_f32 v12, v12, v138, v139
	v_max3_f32 v12, v12, v140, v141
	v_max3_f32 v12, v12, v142, v143
	v_max3_f32 v12, v12, v112, v113
	v_max3_f32 v12, v12, v114, v115
	v_max3_f32 v12, v12, v116, v117
	v_max3_f32 v12, v12, v118, v119
	v_max3_f32 v12, v12, v120, v121
	v_max3_f32 v12, v12, v122, v123
	v_max3_f32 v12, v12, v124, v125
	v_max3_f32 v12, v12, v126, v127
	ds_bpermute_b32 v176, v165, v12
	ds_read2_b64 v[216:219], v243 offset0:128 offset1:130
	ds_read2_b64 v[220:223], v247 offset0:192 offset1:194
	ds_read2_b64 v[224:227], v243 offset0:132 offset1:134
	ds_read2_b64 v[228:231], v247 offset0:196 offset1:198
	ds_read2_b64 v[232:235], v243 offset0:136 offset1:138
	ds_read2_b64 v[236:239], v247 offset0:200 offset1:202
	ds_read2_b64 v[240:243], v243 offset0:140 offset1:142
	ds_read2_b64 v[244:247], v247 offset0:204 offset1:206
	s_waitcnt lgkmcnt(8)
	v_max3_f32 v12, v14, v12, v176
	v_sub_f32_e32 v176, v12, v14
	v_mul_f32_e32 v176, 0x3e38aa3b, v176
	v_cmp_lt_f32_e32 vcc, s51, v176
	s_cbranch_vccnz .LBB0_584
	v_mov_b32_e32 v12, v14
	s_branch .LBB0_585
